# NA step loop: output accumulators stay in v[0:31] (in-place rescale and PV accumulate), 32-48 v_mov_b64 phi copies per step removed, single copy at item exit
# speedup vs baseline: 1.0219x; 1.0003x over previous
.Lna_exit:
	s_nop 11
	v_mov_b64_e32 v[32:33], v[0:1]
	v_mov_b64_e32 v[34:35], v[2:3]
	v_mov_b64_e32 v[36:37], v[4:5]
	v_mov_b64_e32 v[38:39], v[6:7]
	v_mov_b64_e32 v[40:41], v[8:9]
	v_mov_b64_e32 v[42:43], v[10:11]
	v_mov_b64_e32 v[44:45], v[12:13]
	v_mov_b64_e32 v[46:47], v[14:15]
	v_mov_b64_e32 v[48:49], v[16:17]
	v_mov_b64_e32 v[50:51], v[18:19]
	v_mov_b64_e32 v[52:53], v[20:21]
	v_mov_b64_e32 v[54:55], v[22:23]
	v_mov_b64_e32 v[56:57], v[24:25]
	v_mov_b64_e32 v[58:59], v[26:27]
	v_mov_b64_e32 v[60:61], v[28:29]
	v_mov_b64_e32 v[62:63], v[30:31]
	s_branch .LBB0_1068

.LBB0_1086:
	s_cmp_gt_u32 s41, 3
	s_mov_b64 s[12:13], -1
	s_cbranch_scc0 .LBB0_1125
	s_add_i32 s41, s22, s41
	s_add_i32 s42, s41, -4
	v_cmp_ge_i32_e32 vcc, s41, v135
	v_cmp_lt_i32_e64 s[12:13], s42, v136
	s_and_b64 s[12:13], vcc, s[12:13]
	s_andn2_b64 vcc, exec, s[12:13]
	v_mov_b32_e32 v144, v139
	v_mov_b32_e32 v141, v140
	s_cbranch_vccnz .LBB0_1123
	v_add_u32_e32 v36, s40, v114
	v_add_u32_e32 v32, v36, v117
	v_add_u32_e32 v37, v36, v118
	ds_read_b128 v[32:35], v32
	ds_read_b128 v[48:51], v37
	v_add_u32_e32 v37, v36, v119
	v_add_u32_e32 v36, v36, v120
	ds_read_b128 v[52:55], v37
	ds_read_b128 v[56:59], v36
	ds_read2_b32 v[240:241], v138 offset1:1
	ds_read2_b32 v[242:243], v138 offset0:2 offset1:3
	ds_read2_b32 v[244:245], v138 offset0:8 offset1:9
	ds_read2_b32 v[246:247], v138 offset0:10 offset1:11
	ds_read2_b32 v[248:249], v138 offset0:16 offset1:17
	ds_read2_b32 v[250:251], v138 offset0:18 offset1:19
	ds_read2_b32 v[252:253], v138 offset0:24 offset1:25
	ds_read2_b32 v[254:255], v138 offset0:26 offset1:27
	v_cmp_ge_i32_e32 vcc, s41, v134
	v_cmp_lt_i32_e64 s[12:13], s42, v137
	s_and_b64 vcc, vcc, s[12:13]
	v_cndmask_b32_e32 v159, v133, v115, vcc
	v_mov_b32_e32 v157, 0xff800000
	s_waitcnt lgkmcnt(11)
	v_mfma_f32_32x32x16_bf16 v[32:47], v[32:35], v[64:67], 0
	s_waitcnt lgkmcnt(10)
	v_mfma_f32_32x32x16_bf16 v[32:47], v[48:51], v[68:71], v[32:47]
	s_waitcnt lgkmcnt(9)
	v_mfma_f32_32x32x16_bf16 v[32:47], v[52:55], v[72:75], v[32:47]
	s_waitcnt lgkmcnt(0)
	v_cmp_gt_u32_e32 vcc, 16, v159
	v_cndmask_b32_e32 v240, v157, v240, vcc
	v_add_u32_e32 v158, 1, v159
	v_cmp_gt_u32_e32 vcc, 16, v158
	v_cndmask_b32_e32 v241, v157, v241, vcc
	v_add_u32_e32 v158, 2, v159
	v_cmp_gt_u32_e32 vcc, 16, v158
	v_cndmask_b32_e32 v242, v157, v242, vcc
	v_add_u32_e32 v158, 3, v159
	v_cmp_gt_u32_e32 vcc, 16, v158
	v_cndmask_b32_e32 v243, v157, v243, vcc
	v_add_u32_e32 v158, 8, v159
	v_cmp_gt_u32_e32 vcc, 16, v158
	v_cndmask_b32_e32 v244, v157, v244, vcc
	v_add_u32_e32 v158, 9, v159
	v_cmp_gt_u32_e32 vcc, 16, v158
	v_cndmask_b32_e32 v245, v157, v245, vcc
	v_add_u32_e32 v158, 10, v159
	v_cmp_gt_u32_e32 vcc, 16, v158
	v_cndmask_b32_e32 v246, v157, v246, vcc
	v_add_u32_e32 v158, 11, v159
	v_cmp_gt_u32_e32 vcc, 16, v158
	v_cndmask_b32_e32 v247, v157, v247, vcc
	v_mfma_f32_32x32x16_bf16 v[32:47], v[56:59], v[76:79], v[32:47]
	v_cmp_lt_u32_e32 vcc, s36, v159
	v_cndmask_b32_e32 v248, v157, v248, vcc
	v_add_u32_e32 v158, 17, v159
	v_cmp_gt_u32_e32 vcc, 16, v158
	v_cndmask_b32_e32 v249, v157, v249, vcc
	v_add_u32_e32 v158, 18, v159
	v_cmp_gt_u32_e32 vcc, 16, v158
	v_cndmask_b32_e32 v250, v157, v250, vcc
	v_add_u32_e32 v158, 19, v159
	v_cmp_gt_u32_e32 vcc, 16, v158
	v_cndmask_b32_e32 v251, v157, v251, vcc
	v_add_u32_e32 v158, 24, v159
	v_cmp_gt_u32_e32 vcc, 16, v158
	v_cndmask_b32_e32 v252, v157, v252, vcc
	v_add_u32_e32 v158, 25, v159
	v_cmp_gt_u32_e32 vcc, 16, v158
	v_cndmask_b32_e32 v253, v157, v253, vcc
	v_add_u32_e32 v158, 26, v159
	v_cmp_gt_u32_e32 vcc, 16, v158
	v_cndmask_b32_e32 v254, v157, v254, vcc
	v_add_u32_e32 v158, 27, v159
	v_cmp_gt_u32_e32 vcc, 16, v158
	v_cndmask_b32_e32 v255, v157, v255, vcc
	v_add_f32_e32 v142, v32, v240
	v_add_f32_e32 v141, v33, v241
	v_add_f32_e32 v145, v34, v242
	v_add_f32_e32 v143, v35, v243
	v_add_f32_e32 v147, v36, v244
	v_add_f32_e32 v146, v37, v245
	v_add_f32_e32 v149, v38, v246
	v_add_f32_e32 v148, v39, v247
	v_add_f32_e32 v151, v40, v248
	v_add_f32_e32 v150, v41, v249
	v_add_f32_e32 v153, v42, v250
	v_add_f32_e32 v152, v43, v251
	v_add_f32_e32 v155, v44, v252
	v_add_f32_e32 v154, v45, v253
	v_add_f32_e32 v157, v46, v254
	v_add_f32_e32 v156, v47, v255
	v_max3_f32 v32, v142, s37, v141
	v_max3_f32 v32, v32, v145, v143
	v_max3_f32 v32, v32, v147, v146
	v_max3_f32 v32, v32, v149, v148
	v_max3_f32 v32, v32, v151, v150
	v_max3_f32 v32, v32, v153, v152
	v_max3_f32 v32, v32, v155, v154
	v_max3_f32 v32, v32, v157, v156
	v_mov_b32_e32 v33, v32
	s_nop 1
	v_permlane32_swap_b32_e32 v32, v33
	v_max_f32_e32 v33, v33, v33
	v_max_f32_e32 v32, v32, v32
	v_max_f32_e32 v159, v32, v33
	v_add_f32_e32 v32, 0x40b00000, v139
	v_cmp_gt_f32_e32 vcc, v159, v32
	v_mov_b32_e32 v158, v140
	v_mov_b32_e32 v144, v139
	s_cbranch_vccz .LBB0_1122
	v_cndmask_b32_e32 v144, v139, v159, vcc
	v_sub_f32_e32 v32, v139, v144
	v_mul_f32_e32 v32, 0x3fb8aa3b, v32
	v_exp_f32_e32 v158, v32
	s_nop 0
	v_pk_mul_f32 v[30:31], v[30:31], v[158:159] op_sel_hi:[1,0]
	v_pk_mul_f32 v[28:29], v[28:29], v[158:159] op_sel_hi:[1,0]
	v_pk_mul_f32 v[26:27], v[26:27], v[158:159] op_sel_hi:[1,0]
	v_pk_mul_f32 v[24:25], v[24:25], v[158:159] op_sel_hi:[1,0]
	v_pk_mul_f32 v[22:23], v[22:23], v[158:159] op_sel_hi:[1,0]
	v_pk_mul_f32 v[20:21], v[20:21], v[158:159] op_sel_hi:[1,0]
	v_pk_mul_f32 v[18:19], v[18:19], v[158:159] op_sel_hi:[1,0]
	v_pk_mul_f32 v[16:17], v[16:17], v[158:159] op_sel_hi:[1,0]
	v_pk_mul_f32 v[14:15], v[14:15], v[158:159] op_sel_hi:[1,0]
	v_pk_mul_f32 v[12:13], v[12:13], v[158:159] op_sel_hi:[1,0]
	v_pk_mul_f32 v[10:11], v[10:11], v[158:159] op_sel_hi:[1,0]
	v_pk_mul_f32 v[8:9], v[8:9], v[158:159] op_sel_hi:[1,0]
	v_pk_mul_f32 v[6:7], v[6:7], v[158:159] op_sel_hi:[1,0]
	v_pk_mul_f32 v[4:5], v[4:5], v[158:159] op_sel_hi:[1,0]
	v_pk_mul_f32 v[2:3], v[2:3], v[158:159] op_sel_hi:[1,0]
	v_pk_mul_f32 v[0:1], v[0:1], v[158:159] op_sel_hi:[1,0]
	v_mul_f32_e32 v158, v140, v158
.LBB0_1122:
	v_mul_f32_e32 v159, 0xbfb8aa3b, v144
	v_fmamk_f32 v142, v142, 0x3fb8aa3b, v159
	v_exp_f32_e32 v142, v142
	v_fmamk_f32 v141, v141, 0x3fb8aa3b, v159
	v_exp_f32_e32 v160, v141
	v_fmamk_f32 v141, v145, 0x3fb8aa3b, v159
	v_exp_f32_e32 v145, v141
	v_fmamk_f32 v141, v143, 0x3fb8aa3b, v159
	v_exp_f32_e32 v143, v141
	v_fmamk_f32 v147, v147, 0x3fb8aa3b, v159
	v_add_f32_e32 v141, 0, v142
	v_exp_f32_e32 v161, v147
	v_fmamk_f32 v146, v146, 0x3fb8aa3b, v159
	v_add_f32_e32 v141, v160, v141
	v_exp_f32_e32 v162, v146
	v_fmamk_f32 v146, v149, 0x3fb8aa3b, v159
	v_add_f32_e32 v141, v145, v141
	v_exp_f32_e32 v149, v146
	v_fmamk_f32 v146, v148, 0x3fb8aa3b, v159
	v_add_f32_e32 v141, v143, v141
	v_exp_f32_e32 v163, v146
	v_fmamk_f32 v146, v151, 0x3fb8aa3b, v159
	v_add_f32_e32 v141, v161, v141
	v_exp_f32_e32 v151, v146
	v_fmamk_f32 v146, v150, 0x3fb8aa3b, v159
	v_add_f32_e32 v141, v162, v141
	v_exp_f32_e32 v150, v146
	v_fmamk_f32 v146, v153, 0x3fb8aa3b, v159
	v_add_f32_e32 v141, v149, v141
	v_exp_f32_e32 v153, v146
	v_fmamk_f32 v146, v152, 0x3fb8aa3b, v159
	v_add_f32_e32 v141, v163, v141
	v_exp_f32_e32 v152, v146
	v_fmamk_f32 v146, v155, 0x3fb8aa3b, v159
	v_add_f32_e32 v141, v151, v141
	v_exp_f32_e32 v155, v146
	v_fmamk_f32 v146, v154, 0x3fb8aa3b, v159
	v_add_f32_e32 v141, v150, v141
	v_exp_f32_e32 v154, v146
	v_fmamk_f32 v146, v157, 0x3fb8aa3b, v159
	v_add_f32_e32 v141, v153, v141
	v_exp_f32_e32 v157, v146
	v_fmac_f32_e32 v159, 0x3fb8aa3b, v156
	v_add_f32_e32 v141, v152, v141
	v_exp_f32_e32 v156, v159
	v_add_f32_e32 v141, v155, v141
	v_add_f32_e32 v141, v154, v141
	v_add_f32_e32 v141, v157, v141
	v_add_f32_e32 v141, v156, v141
	v_add_f32_e32 v141, v158, v141
	v_cvt_pk_bf16_f32 v146, v142, v160
	v_cvt_pk_bf16_f32 v147, v145, v143
	v_cvt_pk_bf16_f32 v148, v161, v162
	v_cvt_pk_bf16_f32 v149, v149, v163
	v_cvt_pk_bf16_f32 v150, v151, v150
	v_cvt_pk_bf16_f32 v151, v153, v152
	v_cvt_pk_bf16_f32 v152, v155, v154
	v_cvt_pk_bf16_f32 v153, v157, v156
	v_add_u32_e32 v142, s40, v116
	v_add_u32_e32 v142, v142, v125
	v_add_u32_e32 v143, 0x2000, v142
	v_add_u32_e32 v142, 0x3000, v142
	ds_read2_b64 v[154:157], v143 offset1:2
	ds_read2_b64 v[158:161], v143 offset0:4 offset1:6
	ds_read2_b64 v[162:165], v142 offset0:32 offset1:34
	ds_read2_b64 v[166:169], v142 offset0:36 offset1:38
	s_waitcnt lgkmcnt(3)
	v_mfma_f32_32x32x16_bf16 v[0:15], v[154:157], v[146:149], v[0:15]
	s_waitcnt lgkmcnt(1)
	v_mfma_f32_32x32x16_bf16 v[16:31], v[162:165], v[146:149], v[16:31]
	v_mfma_f32_32x32x16_bf16 v[0:15], v[158:161], v[150:153], v[0:15]
	s_waitcnt lgkmcnt(0)
	v_mfma_f32_32x32x16_bf16 v[16:31], v[166:169], v[150:153], v[16:31]

.LBB0_1128:
	v_mul_f32_e32 v141, 0xbfb8aa3b, v139
	v_fmamk_f32 v48, v48, 0x3fb8aa3b, v141
	v_exp_f32_e32 v48, v48
	v_fmamk_f32 v49, v49, 0x3fb8aa3b, v141
	v_exp_f32_e32 v49, v49
	v_fmamk_f32 v50, v50, 0x3fb8aa3b, v141
	v_exp_f32_e32 v50, v50
	v_fmamk_f32 v51, v51, 0x3fb8aa3b, v141
	v_exp_f32_e32 v51, v51
	v_fmamk_f32 v52, v52, 0x3fb8aa3b, v141
	v_add_f32_e32 v142, 0, v48
	v_exp_f32_e32 v52, v52
	v_fmamk_f32 v53, v53, 0x3fb8aa3b, v141
	v_add_f32_e32 v142, v49, v142
	v_exp_f32_e32 v53, v53
	v_fmamk_f32 v54, v54, 0x3fb8aa3b, v141
	v_add_f32_e32 v142, v50, v142
	v_exp_f32_e32 v54, v54
	v_fmamk_f32 v55, v55, 0x3fb8aa3b, v141
	v_add_f32_e32 v142, v51, v142
	v_exp_f32_e32 v55, v55
	v_fmamk_f32 v56, v56, 0x3fb8aa3b, v141
	v_add_f32_e32 v142, v52, v142
	v_exp_f32_e32 v56, v56
	v_fmamk_f32 v57, v57, 0x3fb8aa3b, v141
	v_add_f32_e32 v142, v53, v142
	v_exp_f32_e32 v57, v57
	v_fmamk_f32 v58, v58, 0x3fb8aa3b, v141
	v_add_f32_e32 v142, v54, v142
	v_exp_f32_e32 v58, v58
	v_fmamk_f32 v59, v59, 0x3fb8aa3b, v141
	v_add_f32_e32 v142, v55, v142
	v_exp_f32_e32 v59, v59
	v_fmamk_f32 v60, v60, 0x3fb8aa3b, v141
	v_add_f32_e32 v142, v56, v142
	v_exp_f32_e32 v60, v60
	v_fmamk_f32 v61, v61, 0x3fb8aa3b, v141
	v_add_f32_e32 v142, v57, v142
	v_exp_f32_e32 v61, v61
	v_fmamk_f32 v62, v62, 0x3fb8aa3b, v141
	v_add_f32_e32 v142, v58, v142
	v_exp_f32_e32 v62, v62
	v_fmamk_f32 v63, v63, 0x3fb8aa3b, v141
	v_add_f32_e32 v142, v59, v142
	v_exp_f32_e32 v63, v63
	v_fmamk_f32 v32, v32, 0x3fb8aa3b, v141
	v_add_f32_e32 v142, v60, v142
	v_exp_f32_e32 v143, v32
	v_fmamk_f32 v32, v33, 0x3fb8aa3b, v141
	v_add_f32_e32 v142, v61, v142
	v_exp_f32_e32 v144, v32
	v_fmamk_f32 v32, v34, 0x3fb8aa3b, v141
	v_add_f32_e32 v142, v62, v142
	v_exp_f32_e32 v145, v32
	v_fmamk_f32 v32, v35, 0x3fb8aa3b, v141
	v_add_f32_e32 v142, v63, v142
	v_exp_f32_e32 v146, v32
	v_fmamk_f32 v33, v36, 0x3fb8aa3b, v141
	v_add_f32_e32 v32, v143, v142
	v_exp_f32_e32 v142, v33
	v_fmamk_f32 v33, v37, 0x3fb8aa3b, v141
	v_add_f32_e32 v32, v144, v32
	v_exp_f32_e32 v147, v33
	v_fmamk_f32 v33, v38, 0x3fb8aa3b, v141
	v_add_f32_e32 v32, v145, v32
	v_exp_f32_e32 v148, v33
	v_fmamk_f32 v33, v39, 0x3fb8aa3b, v141
	v_add_f32_e32 v32, v146, v32
	v_exp_f32_e32 v149, v33
	v_fmamk_f32 v33, v40, 0x3fb8aa3b, v141
	v_add_f32_e32 v32, v142, v32
	v_exp_f32_e32 v150, v33
	v_fmamk_f32 v33, v41, 0x3fb8aa3b, v141
	v_add_f32_e32 v32, v147, v32
	v_exp_f32_e32 v151, v33
	v_fmamk_f32 v33, v42, 0x3fb8aa3b, v141
	v_add_f32_e32 v32, v148, v32
	v_exp_f32_e32 v152, v33
	v_fmamk_f32 v33, v43, 0x3fb8aa3b, v141
	v_add_f32_e32 v32, v149, v32
	v_exp_f32_e32 v153, v33
	v_fmamk_f32 v33, v44, 0x3fb8aa3b, v141
	v_add_f32_e32 v32, v150, v32
	v_exp_f32_e32 v154, v33
	v_fmamk_f32 v33, v45, 0x3fb8aa3b, v141
	v_add_f32_e32 v32, v151, v32
	v_exp_f32_e32 v155, v33
	v_fmamk_f32 v33, v46, 0x3fb8aa3b, v141
	v_add_f32_e32 v32, v152, v32
	v_exp_f32_e32 v156, v33
	v_fmac_f32_e32 v141, 0x3fb8aa3b, v47
	v_add_f32_e32 v32, v153, v32
	v_exp_f32_e32 v47, v141
	v_add_f32_e32 v32, v154, v32
	v_add_f32_e32 v32, v155, v32
	v_add_f32_e32 v32, v156, v32
	v_add_f32_e32 v32, v47, v32
	v_add_f32_e32 v141, v140, v32
	v_cvt_pk_bf16_f32 v32, v48, v49
	v_cvt_pk_bf16_f32 v33, v50, v51
	v_cvt_pk_bf16_f32 v34, v52, v53
	v_cvt_pk_bf16_f32 v35, v54, v55
	v_cvt_pk_bf16_f32 v36, v56, v57
	v_cvt_pk_bf16_f32 v37, v58, v59
	v_cvt_pk_bf16_f32 v38, v60, v61
	v_cvt_pk_bf16_f32 v39, v62, v63
	v_cvt_pk_bf16_f32 v40, v143, v144
	v_cvt_pk_bf16_f32 v41, v145, v146
	v_cvt_pk_bf16_f32 v42, v142, v147
	v_cvt_pk_bf16_f32 v43, v148, v149
	v_cvt_pk_bf16_f32 v44, v150, v151
	v_cvt_pk_bf16_f32 v45, v152, v153
	v_cvt_pk_bf16_f32 v46, v154, v155
	v_cvt_pk_bf16_f32 v47, v156, v47
	v_add_u32_e32 v56, s40, v125
	v_add_u32_e32 v140, 0x2000, v56
	v_add_u32_e32 v142, 0x3000, v56
	ds_read2_b64 v[48:51], v140 offset1:2
	ds_read2_b64 v[52:55], v140 offset0:4 offset1:6
	ds_read2_b64 v[56:59], v142 offset0:32 offset1:34
	ds_read2_b64 v[60:63], v142 offset0:36 offset1:38
	s_waitcnt lgkmcnt(3)
	v_mfma_f32_32x32x16_bf16 v[0:15], v[48:51], v[32:35], v[0:15]
	s_waitcnt lgkmcnt(1)
	v_mfma_f32_32x32x16_bf16 v[16:31], v[56:59], v[32:35], v[16:31]
	ds_read2_b64 v[32:35], v140 offset0:8 offset1:10
	ds_read2_b64 v[48:51], v142 offset0:40 offset1:42
	v_mfma_f32_32x32x16_bf16 v[0:15], v[52:55], v[36:39], v[0:15]
	s_waitcnt lgkmcnt(2)
	v_mfma_f32_32x32x16_bf16 v[16:31], v[60:63], v[36:39], v[16:31]
	ds_read2_b64 v[36:39], v140 offset0:12 offset1:14
	ds_read2_b64 v[52:55], v142 offset0:44 offset1:46
	s_waitcnt lgkmcnt(3)
	v_mfma_f32_32x32x16_bf16 v[0:15], v[32:35], v[40:43], v[0:15]
	s_waitcnt lgkmcnt(2)
	v_mfma_f32_32x32x16_bf16 v[16:31], v[48:51], v[40:43], v[16:31]
	s_waitcnt lgkmcnt(1)
	v_mfma_f32_32x32x16_bf16 v[0:15], v[36:39], v[44:47], v[0:15]
	s_waitcnt lgkmcnt(0)
	v_mfma_f32_32x32x16_bf16 v[16:31], v[52:55], v[44:47], v[16:31]
	s_nop 11
	v_mov_b32_e32 v144, v139
	v_add_u32_e32 v138, 0x7c, v138
	s_and_b64 vcc, exec, s[30:31]
	s_cbranch_vccnz .Lna_exit
.LBB0_1129:
	s_nop 4
	v_mov_b32_e32 v139, v144
	v_mov_b32_e32 v140, v141
	s_mov_b32 s41, s39
	s_branch .LBB0_1084
